# speedup vs baseline: 1.0678x; 1.0126x over previous
; __device__ __forceinline__ void phase_A(const Params& p, int l) {
;     ...
;     for (int t = blockIdx.x; t < 64 * 30; t += gridDim.x) {
;         int pm, pn; tile_map(t, 30, pm, pn);
;         const int brow = pm * 256, bcol = pn * 256;
;         f32x4 acc[2][2][4][2];
;         zero_acc(acc);
;         const bool isV = (bcol >= 3584 && bcol < 4096);
;         {
;             gemm256<true, 1024, 1024, 1024>(H + (long)brow * 1024, W + (long)bcol * 1024, acc);
.LBB0_80:
	s_mov_b32 s100, 0
	v_readlane_b32 s0, v234, 6
	v_readlane_b32 s1, v234, 7
	s_andn2_b64 vcc, exec, s[0:1]
	s_mov_b32 s14, s50
	s_cbranch_vccz .LBB0_85
.LBB0_81:
	v_readlane_b32 s0, v234, 46
	s_nop 0
	s_cmp_eq_u32 s0, 0
	s_cbranch_scc1 .Lgd_done
	v_cmp_eq_u32_e32 vcc, 0, v208
	s_and_saveexec_b64 s[98:99], vcc
	s_cbranch_execz .Lgd_join
	s_add_u32 s4, s92, 0xc000
	s_addc_u32 s5, s93, 0
	v_mov_b32_e32 v235, 0
.Lgd_spin:
	global_load_dword v236, v235, s[4:5] sc1
	s_waitcnt vmcnt(0)
	v_cmp_gt_u32_e32 vcc, s54, v236
	s_cbranch_vccz .Lgd_join
	s_sleep 1
	s_branch .Lgd_spin
.Lgd_join:
	s_or_b64 exec, exec, s[98:99]
	s_barrier

; __device__ __forceinline__ int tid_opaque() { int t = threadIdx.x; asm volatile("" : "+v"(t)); return t; }
; __device__ __forceinline__ unsigned xb_add(unsigned* p, unsigned v) { return __hip_atomic_fetch_add(p, v, __ATOMIC_RELAXED, __HIP_MEMORY_SCOPE_AGENT); }
; __device__ __forceinline__ void xcd_barrier(const XcdBarrier& b, unsigned epoch) {
;     asm volatile("s_waitcnt vmcnt(0)" ::: "memory");
;     __syncthreads();
;     if (tid_opaque() == 0) {
;         unsigned* bar = b.bar;
;         unsigned bx = b.x, bnloc = b.nloc, bnx = b.nx;
;         asm volatile("" : "+s"(bar), "+s"(bx), "+s"(bnloc), "+s"(bnx));
;         __builtin_amdgcn_s_waitcnt(0);
;         const unsigned old = xb_add(&bar[XB_XSUB(bx)], 1u);
;         const unsigned gen = epoch;
;         if (old + 1u == (gen + 1u) * bnloc) {
; __global__ void __launch_bounds__(512, 2) mega(Params p) {
;     ...
;         const unsigned e0 = 1u + 5u * (unsigned)l;
;         phase_A(p, l);
;         xcd_barrier(xb, e0);
.LBB0_133:
	s_waitcnt vmcnt(0)
	v_readlane_b32 s0, v234, 46
	v_mov_b32_e32 v0, v208
	s_mul_i32 s0, s0, 2
	s_barrier
	v_writelane_b32 v234, s0, 60
	v_cmp_eq_u32_e32 vcc, 0, v0
	s_and_saveexec_b64 s[0:1], vcc
	s_cbranch_execz .LBB0_163
	s_mov_b32 s4, s51
	v_readlane_b32 s26, v234, 3
	s_mov_b64 s[2:3], s[92:93]
	v_readlane_b32 s6, v234, 2
	s_lshl_b32 s24, s4, 6
	v_readlane_b32 s7, v234, 60
	s_add_i32 s72, s24, 0x500
	s_add_i32 s25, s7, 1
	s_lshl_b64 s[4:5], s[72:73], 2
	s_add_u32 s4, s2, s4
	s_addc_u32 s5, s3, s5
	v_mov_b64_e32 v[0:1], s[4:5]
	s_waitcnt vmcnt(0) expcnt(0) lgkmcnt(0)
	flat_atomic_add v0, v[0:1], v210 sc0
	s_add_i32 s27, s7, 2
	s_mul_i32 s6, s6, s27
	s_waitcnt vmcnt(0) lgkmcnt(0)
	v_add_u32_e32 v0, 1, v0
	v_cmp_ne_u32_e32 vcc, s6, v0
	s_and_saveexec_b64 s[4:5], vcc
	s_xor_b64 s[4:5], exec, s[4:5]
	s_cbranch_execz .LBB0_147
	s_add_i32 s72, s24, 0x900
	s_lshl_b64 s[6:7], s[72:73], 2
	s_add_u32 s8, s2, s6
	s_addc_u32 s9, s3, s7
	v_mov_b64_e32 v[0:1], s[8:9]
	flat_load_dword v0, v[0:1] sc1
	s_waitcnt vmcnt(0) lgkmcnt(0)
	v_cmp_eq_u32_e32 vcc, s25, v0
	s_and_saveexec_b64 s[6:7], vcc
	s_cbranch_execz .LBB0_146
	s_mov_b32 s28, 1
	s_mov_b64 s[10:11], 0
	s_branch .LBB0_138

; __device__ __forceinline__ int tid_opaque() { int t = threadIdx.x; asm volatile("" : "+v"(t)); return t; }
; __device__ __forceinline__ unsigned xb_add(unsigned* p, unsigned v) { return __hip_atomic_fetch_add(p, v, __ATOMIC_RELAXED, __HIP_MEMORY_SCOPE_AGENT); }
; __device__ __forceinline__ void xcd_barrier(const XcdBarrier& b, unsigned epoch) {
;     asm volatile("s_waitcnt vmcnt(0)" ::: "memory");
;     __syncthreads();
;     if (tid_opaque() == 0) {
;         unsigned* bar = b.bar;
;         unsigned bx = b.x, bnloc = b.nloc, bnx = b.nx;
;         asm volatile("" : "+s"(bar), "+s"(bx), "+s"(bnloc), "+s"(bnx));
;         __builtin_amdgcn_s_waitcnt(0);
;         const unsigned old = xb_add(&bar[XB_XSUB(bx)], 1u);
;         const unsigned gen = epoch;
;         if (old + 1u == (gen + 1u) * bnloc) {
; __device__ __forceinline__ void phase_E(const Params& p, int l) {
;     ...
;     for (int it = blockIdx.x; it < NIT + nextra; it += gridDim.x) {
;         if (it >= NIT) { convert_weights_tile(p, 1, it - NIT); continue; }
.LBB0_334:
	s_cmp_lg_u32 s100, 0
	s_cbranch_scc1 .Lwin_done
	v_readlane_b32 s0, v234, 46
	s_nop 0
	s_cmp_lg_u32 s0, 0
	s_cbranch_scc1 .Lwin_done
	s_mov_b32 s100, 1
	s_add_i32 s3, s50, 0x200
	s_movk_i32 s2, 0x3e0
	s_branch .LBB0_517
.Lwin_done:
	s_mov_b32 s100, 0
	s_waitcnt vmcnt(0)
	v_mov_b32_e32 v0, v208
	s_barrier
	s_nop 0
	v_cmp_eq_u32_e32 vcc, 0, v0
	s_and_saveexec_b64 s[0:1], vcc
	s_cbranch_execz .LBB0_364
	s_mov_b64 s[2:3], s[92:93]
	v_readlane_b32 s6, v234, 2
	s_mov_b32 s4, s51
	v_readlane_b32 s28, v234, 3
	s_lshl_b32 s26, s4, 6
	v_readlane_b32 s7, v234, 60
	s_add_i32 s72, s26, 0x500
	s_add_i32 s27, s7, 2
	s_lshl_b64 s[4:5], s[72:73], 2
	s_add_u32 s4, s2, s4
	s_addc_u32 s5, s3, s5
	v_mov_b64_e32 v[0:1], s[4:5]
	s_waitcnt vmcnt(0) expcnt(0) lgkmcnt(0)
	flat_atomic_add v0, v[0:1], v210 sc0
	s_add_i32 s29, s7, 3
	s_mul_i32 s6, s6, s29
	s_waitcnt vmcnt(0) lgkmcnt(0)
	v_add_u32_e32 v0, 1, v0
	v_cmp_ne_u32_e32 vcc, s6, v0
	s_and_saveexec_b64 s[4:5], vcc
	s_xor_b64 s[4:5], exec, s[4:5]
	s_cbranch_execz .LBB0_348
	s_add_i32 s72, s26, 0x900
	s_lshl_b64 s[6:7], s[72:73], 2
	s_add_u32 s10, s2, s6
	s_addc_u32 s11, s3, s7
	v_mov_b64_e32 v[0:1], s[10:11]
	flat_load_dword v0, v[0:1] sc1
	s_waitcnt vmcnt(0) lgkmcnt(0)
	v_cmp_eq_u32_e32 vcc, s27, v0
	s_and_saveexec_b64 s[6:7], vcc
	s_cbranch_execz .LBB0_347
	s_mov_b32 s30, 1
	s_mov_b64 s[12:13], 0
	s_branch .LBB0_339

; __device__ __forceinline__ int tid_opaque() { int t = threadIdx.x; asm volatile("" : "+v"(t)); return t; }
; __device__ __forceinline__ void xcd_barrier(const XcdBarrier& b, unsigned epoch) {
;     asm volatile("s_waitcnt vmcnt(0)" ::: "memory");
;     __syncthreads();
;     if (tid_opaque() == 0) {
; __global__ void __launch_bounds__(512, 2) mega(Params p) {
;     ...
;         phase_GC(p, l);
;         xcd_barrier(xb, e0 + 2u);
.LBB0_367:
	s_waitcnt vmcnt(0)
	v_mov_b32_e32 v0, v208
	s_barrier
	s_nop 0
	v_cmp_eq_u32_e32 vcc, 0, v0
	s_and_saveexec_b64 s[0:1], vcc
	s_cbranch_execz .LBB0_456
	v_readlane_b32 s4, v234, 46
	s_lshl_b32 s4, s4, 8
	s_and_b32 s5, s50, 63
	s_add_i32 s4, s4, s5
	s_add_i32 s4, s4, 0
	s_lshl_b32 s4, s4, 6
	s_add_i32 s4, s4, 0x4000
	s_add_u32 s4, s92, s4
	s_addc_u32 s5, s93, 0
	v_mov_b32_e32 v0, 0
	s_waitcnt vmcnt(0) lgkmcnt(0)
	global_atomic_add v0, v210, s[4:5]
	s_waitcnt vmcnt(0)

; __device__ __forceinline__ int tid_opaque() { int t = threadIdx.x; asm volatile("" : "+v"(t)); return t; }
; __device__ __forceinline__ void xcd_barrier(const XcdBarrier& b, unsigned epoch) {
;     asm volatile("s_waitcnt vmcnt(0)" ::: "memory");
;     __syncthreads();
;     if (tid_opaque() == 0) {
; __global__ void __launch_bounds__(512, 2) mega(Params p) {
;     ...
;         phase_D(p, l);
;         xcd_barrier(xb, e0 + 3u);
.LBB0_482:
	s_waitcnt vmcnt(0)
	v_mov_b32_e32 v0, v208
	s_barrier
	s_nop 0
	v_cmp_eq_u32_e32 vcc, 0, v0
	s_and_saveexec_b64 s[0:1], vcc
	s_cbranch_execz .LBB0_512
	v_readlane_b32 s4, v234, 46
	s_lshl_b32 s4, s4, 8
	s_and_b32 s5, s50, 63
	s_add_i32 s4, s4, s5
	s_add_i32 s4, s4, 64
	s_lshl_b32 s4, s4, 6
	s_add_i32 s4, s4, 0x4000
	s_add_u32 s4, s92, s4
	s_addc_u32 s5, s93, 0
	v_mov_b32_e32 v0, 0
	s_waitcnt vmcnt(0) lgkmcnt(0)
	s_add_u32 s6, s92, 0xc000
	s_addc_u32 s7, s93, 0
	global_atomic_add v0, v210, s[6:7]
	global_atomic_add v0, v210, s[4:5]
	s_waitcnt vmcnt(0)

; __device__ __forceinline__ int tid_opaque() { int t = threadIdx.x; asm volatile("" : "+v"(t)); return t; }
; __device__ __forceinline__ void phase_E(const Params& p, int l) {
;     const bf16_t* P1 = (const bf16_t*)(p.ws + WS_P1);
;     const float* PART = (const float*)(p.ws + WS_PART);
;     const float* xin = (l == 0) ? p.x : p.out;
;     const float* gpost = p.norm_post + l * 1024;
;     const int etid = tid_opaque(); const int lane = etid & 63, wv = etid >> 6;
;     const int nextra = (l == 0) ? NWT_IN : 0;
;     constexpr int RPW = 4;
;     constexpr int NIT = M_ / (8 * RPW);
;     for (int it = blockIdx.x; it < NIT + nextra; it += gridDim.x) {
;         if (it >= NIT) { convert_weights_tile(p, 1, it - NIT); continue; }
;         const int rowb = it * 8 * RPW + wv * RPW;
;         float ps[RPW]; uint2 ov[RPW][4]; float4 xv[RPW][4];
; #pragma unroll
;         for (int r = 0; r < RPW; ++r) {
;             const int row = rowb + r;
;             ps[r] = (lane < 16) ? PART[(long)row * 16 + lane] : 0.f;
; #pragma unroll
;             for (int i = 0; i < 4; ++i) {
;                 const int c = lane * 4 + 256 * i;
;                 ov[r][i] = ld_nt_u2(P1 + (long)row * P1W + 2560 + c);
;                 xv[r][i] = ld_nt_f4(xin + (long)row * 1024 + c);
;             }
;         }
;         float4 gg[4];
; #pragma unroll
;         for (int i = 0; i < 4; ++i) gg[i] = *reinterpret_cast<const float4*>(gpost + lane * 4 + 256 * i);
.LBB0_512:
	s_or_b64 exec, exec, s[0:1]
	v_readlane_b32 s4, v234, 47
	v_readlane_b32 s5, v234, 48
	s_and_b64 s[0:1], s[4:5], exec
	s_movk_i32 s0, 0x200
	s_cselect_b32 s2, s0, 0x200
	s_mov_b64 s[0:1], s[4:5]
	v_mov_b32_e32 v0, v208
	s_cmp_ge_i32 s50, s2
	s_waitcnt lgkmcnt(0)
	s_barrier
	s_cbranch_scc1 .LBB0_542
	v_readlane_b32 s4, v234, 28
	s_and_b64 s[0:1], s[0:1], exec
	v_readlane_b32 s5, v234, 29
	s_mov_b64 s[0:1], s[4:5]
	v_readlane_b32 s3, v234, 46
	s_cselect_b32 s1, s1, s45
	s_cselect_b32 s0, s0, s44
	s_lshl_b32 s72, s3, 10
	s_lshl_b64 s[4:5], s[72:73], 2
	v_and_b32_e32 v2, 63, v0
	s_add_u32 s4, s42, s4
	s_addc_u32 s5, s43, s5
	v_lshlrev_b32_e32 v80, 2, v2
	v_lshlrev_b32_e32 v128, 4, v2
	v_ashrrev_i32_e32 v0, 4, v0
	v_lshl_add_u64 v[84:85], s[4:5], 0, v[128:129]
	v_or_b32_e32 v86, 0x100, v80
	v_readlane_b32 s4, v234, 26
	v_and_b32_e32 v3, -4, v0
	v_or_b32_e32 v88, 0x200, v80
	v_readlane_b32 s5, v234, 27
	v_lshlrev_b32_e32 v0, 2, v86
	v_mov_b32_e32 v1, v129
	v_or_b32_e32 v90, 0x300, v80
	v_lshl_add_u64 v[94:95], s[4:5], 0, v[0:1]
	v_lshlrev_b32_e32 v0, 2, v88
	v_readlane_b32 s6, v234, 30
	v_readlane_b32 s7, v234, 31
	v_mov_b32_e32 v81, v129
	v_lshl_add_u64 v[92:93], s[4:5], 0, v[128:129]
	v_lshl_add_u64 v[96:97], s[4:5], 0, v[0:1]
	v_lshlrev_b32_e32 v0, 2, v90
	v_lshl_add_u64 v[100:101], s[0:1], 0, v[128:129]
	v_lshlrev_b32_e32 v128, 3, v2
	s_and_b32 s98, s50, 7
	s_lshl_b32 s98, s98, 11
	s_lshr_b32 s99, s50, 3
	s_and_b32 s99, s99, 7
	s_lshl_b32 s99, s99, 8
	s_add_i32 s98, s98, s99
	s_lshr_b32 s99, s50, 6
	s_lshl_b32 s99, s99, 6
	s_add_i32 s0, s98, s99
	v_cmp_gt_u32_e64 s[6:7], 16, v2
	v_lshl_add_u64 v[82:83], s[96:97], 0, v[80:81]
	v_lshl_add_u64 v[98:99], s[4:5], 0, v[0:1]
	v_lshl_add_u64 v[102:103], s[74:75], 0, v[128:129]
	v_add_u32_e32 v104, s0, v3
	s_mov_b32 s3, s50
	v_readlane_b32 s8, v234, 32
	v_readlane_b32 s9, v234, 33
	v_readlane_b32 s10, v234, 34
	v_readlane_b32 s11, v234, 35
	s_branch .LBB0_517

; __device__ __forceinline__ void phase_E(const Params& p, int l) {
;     ...
;     for (int it = blockIdx.x; it < NIT + nextra; it += gridDim.x) {
;         if (it >= NIT) { convert_weights_tile(p, 1, it - NIT); continue; }
; __global__ void __launch_bounds__(512, 2) mega(Params p) {
;     ...
;         phase_E(p, l);
;         if (l == 0) xcd_barrier(xb, e0 + 4u);
.LBB0_541:
	s_cmp_lg_u32 s100, 0
	s_cbranch_scc1 .LBB0_334
	v_readlane_b32 s0, v234, 47
	v_readlane_b32 s1, v234, 48
.LBB0_542:
	s_andn2_b64 vcc, exec, s[0:1]
	s_mov_b64 s[0:1], -1
	s_cbranch_vccnz .LBB0_79
	s_waitcnt vmcnt(0)
	v_mov_b32_e32 v0, v208
	s_barrier
	s_nop 0
	v_cmp_eq_u32_e32 vcc, 0, v0
	s_and_saveexec_b64 s[0:1], vcc
	s_cbranch_execz .LBB0_78
	v_readlane_b32 s4, v234, 46
	s_lshl_b32 s4, s4, 8
	s_and_b32 s5, s50, 63
	s_add_i32 s4, s4, s5
	s_add_i32 s4, s4, 128
	s_lshl_b32 s4, s4, 6
	s_add_i32 s4, s4, 0x4000
	s_add_u32 s4, s92, s4
	s_addc_u32 s5, s93, 0
	v_mov_b32_e32 v0, 0
	s_waitcnt vmcnt(0) lgkmcnt(0)
	global_atomic_add v0, v210, s[4:5]
	s_waitcnt vmcnt(0)

; __device__ __forceinline__ unsigned xb_ld(unsigned* p) { return __hip_atomic_load(p, __ATOMIC_RELAXED, __HIP_MEMORY_SCOPE_AGENT); }
; __device__ __forceinline__ unsigned xb_add(unsigned* p, unsigned v) { return __hip_atomic_fetch_add(p, v, __ATOMIC_RELAXED, __HIP_MEMORY_SCOPE_AGENT); }
; __device__ __forceinline__ void xcd_barrier(const XcdBarrier& b, unsigned epoch) {
;     ...
;         unsigned* bar = b.bar;
;         unsigned bx = b.x, bnloc = b.nloc, bnx = b.nx;
;         asm volatile("" : "+s"(bar), "+s"(bx), "+s"(bnloc), "+s"(bnx));
;         __builtin_amdgcn_s_waitcnt(0);
;         const unsigned old = xb_add(&bar[XB_XSUB(bx)], 1u);
;         const unsigned gen = epoch;
;         if (old + 1u == (gen + 1u) * bnloc) {
;             __builtin_amdgcn_fence(__ATOMIC_RELEASE, "agent");
;             asm volatile("s_waitcnt vmcnt(0)" ::: "memory");
;             const unsigned og = xb_add(&bar[XB_TOP], 1u);
;             const unsigned tg = epoch;
;             if (og + 1u == (tg + 1u) * bnx) xb_add(&bar[XB_TOPGEN], 1u);
;             else XB_SPIN(xb_ld(&bar[XB_TOPGEN]) == tg, bar);
;             __builtin_amdgcn_fence(__ATOMIC_ACQUIRE, "agent");
;             xb_add(&bar[XB_XGEN(bx)], 1u);
.Lgbc_done:
	buffer_inv sc1
	s_branch .LBB0_78
	s_mov_b32 s4, s51
	v_readlane_b32 s25, v234, 3
	s_mov_b64 s[2:3], s[92:93]
	v_readlane_b32 s6, v234, 2
	s_lshl_b32 s24, s4, 6
	s_add_i32 s72, s24, 0x500
	s_lshl_b64 s[4:5], s[72:73], 2
	s_add_u32 s4, s2, s4
	s_addc_u32 s5, s3, s5
	v_mov_b64_e32 v[0:1], s[4:5]
	s_waitcnt vmcnt(0) expcnt(0) lgkmcnt(0)
	flat_atomic_add v0, v[0:1], v210 sc0
	s_mul_i32 s6, s6, 4
	s_waitcnt vmcnt(0) lgkmcnt(0)
	v_add_u32_e32 v0, 1, v0
	v_cmp_ne_u32_e32 vcc, s6, v0
	s_and_saveexec_b64 s[4:5], vcc
	s_xor_b64 s[4:5], exec, s[4:5]
	s_cbranch_execz .LBB0_557
	s_add_i32 s72, s24, 0x900
	s_lshl_b64 s[6:7], s[72:73], 2
	s_add_u32 s8, s2, s6
	s_addc_u32 s9, s3, s7
	v_mov_b64_e32 v[0:1], s[8:9]
	flat_load_dword v0, v[0:1] sc1
	s_waitcnt vmcnt(0) lgkmcnt(0)
	v_cmp_eq_u32_e32 vcc, 3, v0
	s_and_saveexec_b64 s[6:7], vcc
	s_cbranch_execz .LBB0_556
	s_mov_b32 s26, 1
	s_mov_b64 s[10:11], 0
	s_branch .LBB0_548

; __global__ void __launch_bounds__(512, 2) mega(Params p) {
;     cg::grid_group grid = cg::this_grid();
;     ...
;     phase_prep(p);
;     if (p.never) grid.sync();
;     xcd_barrier(xb, 0u);
; #pragma unroll 1
;     for (int l = 0; l < 2; ++l) {
;         const unsigned e0 = 1u + 5u * (unsigned)l;
;         phase_A(p, l);
;         xcd_barrier(xb, e0);
;         phase_B(p, l);
;         xcd_barrier(xb, e0 + 1u);
;         phase_GC(p, l);
;         xcd_barrier(xb, e0 + 2u);
;         phase_D(p, l);
;         xcd_barrier(xb, e0 + 3u);
;         phase_E(p, l);
;         if (l == 0) xcd_barrier(xb, e0 + 4u);
;     }
; }
	.amdhsa_kernel _Z4mega6Params
		.amdhsa_group_segment_fixed_size 0
		.amdhsa_private_segment_fixed_size 0
		.amdhsa_kernarg_size 400
		.amdhsa_user_sgpr_count 2
		.amdhsa_user_sgpr_dispatch_ptr 0
		.amdhsa_user_sgpr_queue_ptr 0
		.amdhsa_user_sgpr_kernarg_segment_ptr 1
		.amdhsa_user_sgpr_dispatch_id 0
		.amdhsa_user_sgpr_kernarg_preload_length 0
		.amdhsa_user_sgpr_kernarg_preload_offset 0
		.amdhsa_user_sgpr_private_segment_size 0
		.amdhsa_uses_dynamic_stack 0
		.amdhsa_enable_private_segment 0
		.amdhsa_system_sgpr_workgroup_id_x 1
		.amdhsa_system_sgpr_workgroup_id_y 0
		.amdhsa_system_sgpr_workgroup_id_z 0
		.amdhsa_system_sgpr_workgroup_info 0
		.amdhsa_system_vgpr_workitem_id 2
		.amdhsa_next_free_vgpr 237
		.amdhsa_next_free_sgpr 102
		.amdhsa_accum_offset 240
		.amdhsa_reserve_vcc 1
		.amdhsa_float_round_mode_32 0
		.amdhsa_float_round_mode_16_64 0
		.amdhsa_float_denorm_mode_32 3
		.amdhsa_float_denorm_mode_16_64 3
		.amdhsa_dx10_clamp 1
		.amdhsa_ieee_mode 1
		.amdhsa_fp16_overflow 0
		.amdhsa_tg_split 0
		.amdhsa_exception_fp_ieee_invalid_op 0
		.amdhsa_exception_fp_denorm_src 0
		.amdhsa_exception_fp_ieee_div_zero 0
		.amdhsa_exception_fp_ieee_overflow 0
		.amdhsa_exception_fp_ieee_underflow 0
		.amdhsa_exception_fp_ieee_inexact 0
		.amdhsa_exception_int_div_zero 0
	.end_amdhsa_kernel

; __global__ void __launch_bounds__(512, 2) mega(Params p) {
.Lfunc_end0:
	.size	_Z4mega6Params, .Lfunc_end0-_Z4mega6Params
	.set _Z4mega6Params.num_vgpr, 237
	.set _Z4mega6Params.num_agpr, 0
	.set _Z4mega6Params.numbered_sgpr, 98
	.set _Z4mega6Params.num_named_barrier, 0
	.set _Z4mega6Params.private_seg_size, 0
	.set _Z4mega6Params.uses_vcc, 1
	.set _Z4mega6Params.uses_flat_scratch, 0
	.set _Z4mega6Params.has_dyn_sized_stack, 0
	.set _Z4mega6Params.has_recursion, 0
	.set _Z4mega6Params.has_indirect_call, 0

; __global__ void __launch_bounds__(512, 2) mega(Params p) {
amdhsa.kernels:
  - .agpr_count:     0
    .args:
      - .offset:         0
        .size:           144
        .value_kind:     by_value
      - .offset:         144
        .size:           4
        .value_kind:     hidden_block_count_x
      - .offset:         148
        .size:           4
        .value_kind:     hidden_block_count_y
      - .offset:         152
        .size:           4
        .value_kind:     hidden_block_count_z
      - .offset:         156
        .size:           2
        .value_kind:     hidden_group_size_x
      - .offset:         158
        .size:           2
        .value_kind:     hidden_group_size_y
      - .offset:         160
        .size:           2
        .value_kind:     hidden_group_size_z
      - .offset:         162
        .size:           2
        .value_kind:     hidden_remainder_x
      - .offset:         164
        .size:           2
        .value_kind:     hidden_remainder_y
      - .offset:         166
        .size:           2
        .value_kind:     hidden_remainder_z
      - .offset:         184
        .size:           8
        .value_kind:     hidden_global_offset_x
      - .offset:         192
        .size:           8
        .value_kind:     hidden_global_offset_y
      - .offset:         200
        .size:           8
        .value_kind:     hidden_global_offset_z
      - .offset:         208
        .size:           2
        .value_kind:     hidden_grid_dims
      - .offset:         232
        .size:           8
        .value_kind:     hidden_multigrid_sync_arg
      - .offset:         264
        .size:           4
        .value_kind:     hidden_dynamic_lds_size
    .group_segment_fixed_size: 0
    .kernarg_segment_align: 8
    .kernarg_segment_size: 400
    .language:       OpenCL C
    .language_version:
      - 2
      - 0
    .max_flat_workgroup_size: 512
    .name:           _Z4mega6Params
    .private_segment_fixed_size: 0
    .sgpr_count:     108
    .sgpr_spill_count: 64
    .symbol:         _Z4mega6Params.kd
    .uniform_work_group_size: 1
    .uses_dynamic_stack: false
    .vgpr_count:     237
    .vgpr_spill_count: 0
    .wavefront_size: 64
